# 7.11 back-edge rotation of the FoX tile loop: ring rotation, counters, exit test and next slot-address prelude moved in front of the loop-back barrier
# speedup vs baseline: 1.0060x; 1.0023x over previous
.Lyp649:
	s_branch .LBB0_649
.LBB0_649:
	s_add_i32 s27, s0, -2
	s_and_b32 s27, s27, 1
	s_xor_b32 s34, s27, 1
	s_mul_i32 s35, s34, 0x4400
	s_add_i32 s35, s35, 0
	s_mulk_i32 s34, 0xc00
	s_add_i32 s34, s35, s34
	v_add3_u32 v0, s35, v157, v158
.Lff1a_top2:
	s_waitcnt vmcnt(3)
	ds_write_b128 v0, v[130:133]
	v_add3_u32 v0, s68, v159, v158
	s_waitcnt vmcnt(2)
	ds_write_b128 v0, v[134:137] offset:34816
	v_add3_u32 v0, s35, v160, v161
	s_cmp_lt_u32 s0, s1
	s_waitcnt vmcnt(1)
	ds_write_b128 v0, v[138:141]
	v_add3_u32 v0, s68, v147, v161
	s_cselect_b32 s34, s0, s6
	s_sub_i32 s34, s6, s34
	s_lshl_b32 s34, s34, 20
	s_add_u32 s80, s78, s34
	s_addc_u32 s81, s79, 0
	s_add_u32 s80, s80, 0x1000
	s_addc_u32 s81, s81, 0
	s_add_u32 s82, s80, 0x1000
	s_addc_u32 s83, s81, 0
	s_waitcnt vmcnt(0)
	ds_write_b128 v0, v[142:145] offset:34816
	global_load_dwordx4 v[130:133], v150, s[80:81]
	global_load_dwordx4 v[134:137], v150, s[82:83]
	s_sub_i32 s34, s26, 63
	s_cmp_gt_i32 s34, s5
	global_load_dwordx4 v[138:141], v152, s[80:81]
	global_load_dwordx4 v[142:145], v152, s[82:83]
	s_lshr_b32 s77, s7, 2
	s_sub_i32 s77, s77, s26
	s_add_i32 s77, s77, -1
	s_sub_i32 s75, s7, s4
	s_add_i32 s75, s75, -256
	s_cmp_gt_i32 s77, s5
	s_cbranch_scc1 .Lff1a_inact
	s_cmp_eq_u32 s72, 0
	s_cbranch_scc1 .Lff1a_first
	s_mul_i32 s34, s27, 0x4400
	v_add_u32_e32 v0, s34, v162
	ds_read_b128 v[198:201], v0
	ds_read_b128 v[202:205], v0 offset:32
	ds_read_b128 v[206:209], v0 offset:8704
	ds_read_b128 v[210:213], v0 offset:8736
	v_add_u32_e32 v246, s75, v149
	v_add_u32_e32 v234, 0x12800, v246
	v_add_u32_e32 v235, 0x12880, v246
	v_add_u32_e32 v238, 0x12820, v246
	v_add_u32_e32 v239, 0x128a0, v246
	v_add_u32_e32 v242, 0x12840, v246
	v_add_u32_e32 v243, 0x128c0, v246
	v_add_u32_e32 v247, 0x12860, v246
	v_add_u32_e32 v246, 0x128e0, v246
	ds_read_b128 v[218:221], v234
	ds_read_b128 v[234:237], v235
	ds_read_b128 v[222:225], v238
	ds_read_b128 v[238:241], v239
	ds_read_b128 v[226:229], v242
	ds_read_b128 v[242:245], v243
	ds_read_b128 v[230:233], v247
	ds_read_b128 v[246:249], v246
	s_waitcnt lgkmcnt(1)
	v_mfma_f32_32x32x16_bf16 v[218:233], v[198:201], v[98:101], v[218:233]
	v_sub_f32_e32 v82, v82, v197
	v_sub_f32_e32 v83, v83, v197
	v_sub_f32_e32 v84, v84, v197
	v_sub_f32_e32 v85, v85, v197
	v_exp_f32_e32 v82, v82
	v_exp_f32_e32 v83, v83
	v_exp_f32_e32 v84, v84
	v_exp_f32_e32 v85, v85
	s_waitcnt lgkmcnt(0)
	v_mfma_f32_32x32x16_bf16 v[234:249], v[206:209], v[98:101], v[234:249]
	v_sub_f32_e32 v86, v86, v197
	v_sub_f32_e32 v87, v87, v197
	v_sub_f32_e32 v88, v88, v197
	v_sub_f32_e32 v89, v89, v197
	v_exp_f32_e32 v86, v86
	v_exp_f32_e32 v87, v87
	v_exp_f32_e32 v88, v88
	v_exp_f32_e32 v89, v89
	v_mfma_f32_32x32x16_bf16 v[218:233], v[202:205], v[102:105], v[218:233]
	v_sub_f32_e32 v66, v66, v197
	v_sub_f32_e32 v67, v67, v197
	v_sub_f32_e32 v68, v68, v197
	v_sub_f32_e32 v69, v69, v197
	v_exp_f32_e32 v66, v66
	v_exp_f32_e32 v67, v67
	v_exp_f32_e32 v68, v68
	v_exp_f32_e32 v69, v69
	ds_read_b128 v[198:201], v0 offset:64
	ds_read_b128 v[202:205], v0 offset:96
	ds_read_b128 v[206:209], v0 offset:8768
	ds_read_b128 v[214:217], v0 offset:8800
	v_mfma_f32_32x32x16_bf16 v[234:249], v[210:213], v[102:105], v[234:249]
	v_add_f32_e32 v250, v82, v86
	v_add_f32_e32 v251, v83, v87
	v_add_f32_e32 v252, v84, v88
	v_add_f32_e32 v253, v85, v89
	v_sub_f32_e32 v70, v70, v197
	v_sub_f32_e32 v71, v71, v197
	v_sub_f32_e32 v72, v72, v197
	v_sub_f32_e32 v73, v73, v197
	s_waitcnt lgkmcnt(3)
	v_mfma_f32_32x32x16_bf16 v[218:233], v[198:201], v[106:109], v[218:233]
	v_exp_f32_e32 v70, v70
	v_exp_f32_e32 v71, v71
	v_exp_f32_e32 v72, v72
	v_exp_f32_e32 v73, v73
	v_add_f32_e32 v250, v250, v66
	v_add_f32_e32 v251, v251, v67
	v_add_f32_e32 v252, v252, v68
	v_add_f32_e32 v253, v253, v69
	s_waitcnt lgkmcnt(1)
	v_mfma_f32_32x32x16_bf16 v[234:249], v[206:209], v[106:109], v[234:249]
	v_sub_f32_e32 v90, v90, v197
	v_sub_f32_e32 v91, v91, v197
	v_sub_f32_e32 v92, v92, v197
	v_sub_f32_e32 v93, v93, v197
	v_exp_f32_e32 v90, v90
	v_exp_f32_e32 v91, v91
	v_exp_f32_e32 v92, v92
	v_exp_f32_e32 v93, v93
	v_mfma_f32_32x32x16_bf16 v[218:233], v[202:205], v[110:113], v[218:233]
	v_add_f32_e32 v250, v250, v70
	v_add_f32_e32 v251, v251, v71
	v_add_f32_e32 v252, v252, v72
	v_add_f32_e32 v253, v253, v73
	v_sub_f32_e32 v94, v94, v197
	v_sub_f32_e32 v95, v95, v197
	v_sub_f32_e32 v96, v96, v197
	v_sub_f32_e32 v97, v97, v197
	ds_read_b128 v[198:201], v0 offset:128
	ds_read_b128 v[202:205], v0 offset:160
	ds_read_b128 v[206:209], v0 offset:8832
	ds_read_b128 v[210:213], v0 offset:8864
	s_waitcnt lgkmcnt(4)
	v_mfma_f32_32x32x16_bf16 v[234:249], v[214:217], v[110:113], v[234:249]
	v_exp_f32_e32 v94, v94
	v_exp_f32_e32 v95, v95
	v_exp_f32_e32 v96, v96
	v_exp_f32_e32 v97, v97
	v_add_f32_e32 v250, v250, v90
	v_add_f32_e32 v251, v251, v91
	v_add_f32_e32 v252, v252, v92
	v_add_f32_e32 v253, v253, v93
	s_waitcnt lgkmcnt(3)
	v_mfma_f32_32x32x16_bf16 v[218:233], v[198:201], v[114:117], v[218:233]
	v_sub_f32_e32 v74, v74, v197
	v_sub_f32_e32 v75, v75, v197
	v_sub_f32_e32 v76, v76, v197
	v_sub_f32_e32 v77, v77, v197
	v_exp_f32_e32 v74, v74
	v_exp_f32_e32 v75, v75
	v_exp_f32_e32 v76, v76
	v_exp_f32_e32 v77, v77
	s_waitcnt lgkmcnt(1)
	v_mfma_f32_32x32x16_bf16 v[234:249], v[206:209], v[114:117], v[234:249]
	v_add_f32_e32 v250, v250, v94
	v_add_f32_e32 v251, v251, v95
	v_add_f32_e32 v252, v252, v96
	v_add_f32_e32 v253, v253, v97
	v_sub_f32_e32 v78, v78, v197
	v_sub_f32_e32 v79, v79, v197
	v_sub_f32_e32 v80, v80, v197
	v_sub_f32_e32 v81, v81, v197
	v_mfma_f32_32x32x16_bf16 v[218:233], v[202:205], v[118:121], v[218:233]
	v_exp_f32_e32 v78, v78
	v_exp_f32_e32 v79, v79
	v_exp_f32_e32 v80, v80
	v_exp_f32_e32 v81, v81
	v_add_f32_e32 v250, v250, v74
	v_add_f32_e32 v251, v251, v75
	v_add_f32_e32 v252, v252, v76
	v_add_f32_e32 v253, v253, v77
	ds_read_b128 v[198:201], v0 offset:192
	ds_read_b128 v[202:205], v0 offset:224
	ds_read_b128 v[206:209], v0 offset:8896
	ds_read_b128 v[214:217], v0 offset:8928
	s_waitcnt lgkmcnt(4)
	v_mfma_f32_32x32x16_bf16 v[234:249], v[210:213], v[118:121], v[234:249]
	v_add_f32_e32 v250, v250, v78
	v_add_f32_e32 v251, v251, v79
	v_add_f32_e32 v252, v252, v80
	v_add_f32_e32 v253, v253, v81
	v_add_f32_e32 v250, v250, v251
	v_add_f32_e32 v252, v252, v253
	v_add_f32_e32 v250, v250, v252
	v_add_f32_e32 v196, v196, v250
	s_waitcnt lgkmcnt(3)
	v_mfma_f32_32x32x16_bf16 v[218:233], v[198:201], v[122:125], v[218:233]
	v_cvt_pk_bf16_f32 v73, v72, v73
	v_cvt_pk_bf16_f32 v72, v70, v71
	v_cvt_pk_bf16_f32 v71, v68, v69
	v_cvt_pk_bf16_f32 v70, v66, v67
	v_cvt_pk_bf16_f32 v66, v82, v83
	v_cvt_pk_bf16_f32 v67, v84, v85
	v_cvt_pk_bf16_f32 v68, v86, v87
	v_cvt_pk_bf16_f32 v69, v88, v89
	s_waitcnt lgkmcnt(1)
	v_mfma_f32_32x32x16_bf16 v[234:249], v[206:209], v[122:125], v[234:249]
	v_cvt_pk_bf16_f32 v81, v80, v81
	v_cvt_pk_bf16_f32 v80, v78, v79
	v_cvt_pk_bf16_f32 v79, v76, v77
	v_cvt_pk_bf16_f32 v78, v74, v75
	v_cvt_pk_bf16_f32 v74, v90, v91
	v_cvt_pk_bf16_f32 v75, v92, v93
	v_cvt_pk_bf16_f32 v76, v94, v95
	v_cvt_pk_bf16_f32 v77, v96, v97
	v_mfma_f32_32x32x16_bf16 v[218:233], v[202:205], v[126:129], v[218:233]
	s_waitcnt lgkmcnt(0)
	v_mfma_f32_32x32x16_bf16 v[234:249], v[214:217], v[126:129], v[234:249]
	s_add_i32 s76, s77, 63
	s_cmp_le_i32 s76, s5
	s_cbranch_scc1 .Lff1a_z2
	v_cmp_le_i32_e32 vcc, v165, v195
	s_nop 8
	v_cndmask_b32_e32 v234, v155, v234, vcc
	v_cmp_lt_i32_e32 vcc, v163, v195
	s_nop 1
	v_cndmask_b32_e32 v219, v155, v219, vcc
	v_cmp_le_i32_e32 vcc, v163, v195
	s_nop 1
	v_cndmask_b32_e32 v218, v155, v218, vcc
	v_cmp_le_i32_e32 vcc, v166, v195
	s_nop 1
	v_cndmask_b32_e32 v235, v155, v235, vcc
	v_cmp_le_i32_e32 vcc, v167, v195
	s_nop 1
	v_cndmask_b32_e32 v220, v155, v220, vcc
	v_cmp_le_i32_e32 vcc, v168, v195
	s_nop 1
	v_cndmask_b32_e32 v236, v155, v236, vcc
	v_cmp_le_i32_e32 vcc, v169, v195
	s_nop 1
	v_cndmask_b32_e32 v221, v155, v221, vcc
	v_cmp_le_i32_e32 vcc, v170, v195
	s_nop 1
	v_cndmask_b32_e32 v237, v155, v237, vcc
	v_cmp_le_i32_e32 vcc, v171, v195
	s_nop 1
	v_cndmask_b32_e32 v222, v155, v222, vcc
	v_cmp_le_i32_e32 vcc, v172, v195
	s_nop 1
	v_cndmask_b32_e32 v238, v155, v238, vcc
	v_cmp_le_i32_e32 vcc, v173, v195
	s_nop 1
	v_cndmask_b32_e32 v223, v155, v223, vcc
	v_cmp_le_i32_e32 vcc, v174, v195
	s_nop 1
	v_cndmask_b32_e32 v239, v155, v239, vcc
	v_cmp_le_i32_e32 vcc, v175, v195
	s_nop 1
	v_cndmask_b32_e32 v224, v155, v224, vcc
	v_cmp_le_i32_e32 vcc, v176, v195
	s_nop 1
	v_cndmask_b32_e32 v240, v155, v240, vcc
	v_cmp_le_i32_e32 vcc, v177, v195
	s_nop 1
	v_cndmask_b32_e32 v225, v155, v225, vcc
	v_cmp_le_i32_e32 vcc, v178, v195
	s_nop 1
	v_cndmask_b32_e32 v241, v155, v241, vcc
	v_cmp_le_i32_e32 vcc, v179, v195
	s_nop 1
	v_cndmask_b32_e32 v226, v155, v226, vcc
	v_cmp_le_i32_e32 vcc, v180, v195
	s_nop 1
	v_cndmask_b32_e32 v242, v155, v242, vcc
	v_cmp_le_i32_e32 vcc, v181, v195
	s_nop 1
	v_cndmask_b32_e32 v227, v155, v227, vcc
	v_cmp_le_i32_e32 vcc, v182, v195
	s_nop 1
	v_cndmask_b32_e32 v243, v155, v243, vcc
	v_cmp_le_i32_e32 vcc, v183, v195
	s_nop 1
	v_cndmask_b32_e32 v228, v155, v228, vcc
	v_cmp_le_i32_e32 vcc, v184, v195
	s_nop 1
	v_cndmask_b32_e32 v244, v155, v244, vcc
	v_cmp_le_i32_e32 vcc, v185, v195
	s_nop 1
	v_cndmask_b32_e32 v229, v155, v229, vcc
	v_cmp_le_i32_e32 vcc, v186, v195
	s_nop 1
	v_cndmask_b32_e32 v245, v155, v245, vcc
	v_cmp_le_i32_e32 vcc, v187, v195
	s_nop 1
	v_cndmask_b32_e32 v230, v155, v230, vcc
	v_cmp_le_i32_e32 vcc, v188, v195
	s_nop 1
	v_cndmask_b32_e32 v246, v155, v246, vcc
	v_cmp_le_i32_e32 vcc, v189, v195
	s_nop 1
	v_cndmask_b32_e32 v231, v155, v231, vcc
	v_cmp_le_i32_e32 vcc, v190, v195
	s_nop 1
	v_cndmask_b32_e32 v247, v155, v247, vcc
	v_cmp_le_i32_e32 vcc, v191, v195
	s_nop 1
	v_cndmask_b32_e32 v232, v155, v232, vcc
	v_cmp_le_i32_e32 vcc, v192, v195
	s_nop 1
	v_cndmask_b32_e32 v248, v155, v248, vcc
	v_cmp_le_i32_e32 vcc, v193, v195
	s_nop 1
	v_cndmask_b32_e32 v233, v155, v233, vcc
	v_cmp_le_i32_e32 vcc, v194, v195
	s_nop 1
	v_cndmask_b32_e32 v249, v155, v249, vcc

.Lff1a_bar:
	s_mov_b32 s71, s70
	s_mov_b32 s70, s69
	s_mov_b32 s69, s68
	s_mov_b32 s68, s71
	s_addk_i32 s4, 0x100
	s_add_i32 s26, s26, 64
	s_add_i32 s0, s0, 1
	v_add_u32_e32 v195, 64, v195
	s_add_i32 s27, s0, -2
	s_and_b32 s27, s27, 1
	s_xor_b32 s34, s27, 1
	s_mul_i32 s35, s34, 0x4400
	s_add_i32 s35, s35, 0
	s_mulk_i32 s34, 0xc00
	s_add_i32 s34, s35, s34
	v_add3_u32 v0, s35, v157, v158
	s_cmp_lg_u32 s7, s4
	s_waitcnt lgkmcnt(0)
	s_barrier
	s_cbranch_scc0 .Lff1a_exit
	s_branch .Lff1b_top2

.Lff1b_top2:
	s_waitcnt vmcnt(3)
	ds_write_b128 v0, v[130:133]
	v_add3_u32 v0, s68, v159, v158
	s_waitcnt vmcnt(2)
	ds_write_b128 v0, v[134:137] offset:34816
	v_add3_u32 v0, s35, v160, v161
	s_cmp_lt_u32 s0, s1
	s_waitcnt vmcnt(1)
	ds_write_b128 v0, v[138:141]
	v_add3_u32 v0, s68, v147, v161
	s_cselect_b32 s34, s0, s6
	s_sub_i32 s34, s6, s34
	s_lshl_b32 s34, s34, 20
	s_add_u32 s80, s78, s34
	s_addc_u32 s81, s79, 0
	s_add_u32 s80, s80, 0x1000
	s_addc_u32 s81, s81, 0
	s_add_u32 s82, s80, 0x1000
	s_addc_u32 s83, s81, 0
	s_waitcnt vmcnt(0)
	ds_write_b128 v0, v[142:145] offset:34816
	global_load_dwordx4 v[130:133], v150, s[80:81]
	global_load_dwordx4 v[134:137], v150, s[82:83]
	s_sub_i32 s34, s26, 63
	s_cmp_gt_i32 s34, s5
	global_load_dwordx4 v[138:141], v152, s[80:81]
	global_load_dwordx4 v[142:145], v152, s[82:83]
	s_lshr_b32 s77, s7, 2
	s_sub_i32 s77, s77, s26
	s_add_i32 s77, s77, -1
	s_sub_i32 s75, s7, s4
	s_add_i32 s75, s75, -256
	s_cmp_gt_i32 s77, s5
	s_cbranch_scc1 .Lff1b_inact
	s_cmp_eq_u32 s72, 0
	s_cbranch_scc1 .Lff1b_first
	s_mul_i32 s34, s27, 0x4400
	v_add_u32_e32 v0, s34, v162
	ds_read_b128 v[198:201], v0
	ds_read_b128 v[202:205], v0 offset:32
	ds_read_b128 v[206:209], v0 offset:8704
	ds_read_b128 v[210:213], v0 offset:8736
	v_add_u32_e32 v78, s75, v149
	v_add_u32_e32 v66, 0x12800, v78
	v_add_u32_e32 v67, 0x12880, v78
	v_add_u32_e32 v70, 0x12820, v78
	v_add_u32_e32 v71, 0x128a0, v78
	v_add_u32_e32 v74, 0x12840, v78
	v_add_u32_e32 v75, 0x128c0, v78
	v_add_u32_e32 v79, 0x12860, v78
	v_add_u32_e32 v78, 0x128e0, v78
	ds_read_b128 v[82:85], v66
	ds_read_b128 v[66:69], v67
	ds_read_b128 v[86:89], v70
	ds_read_b128 v[70:73], v71
	ds_read_b128 v[90:93], v74
	ds_read_b128 v[74:77], v75
	ds_read_b128 v[94:97], v79
	ds_read_b128 v[78:81], v78
	s_waitcnt lgkmcnt(1)
	v_mfma_f32_32x32x16_bf16 v[82:97], v[198:201], v[98:101], v[82:97]
	v_sub_f32_e32 v218, v218, v197
	v_sub_f32_e32 v219, v219, v197
	v_sub_f32_e32 v220, v220, v197
	v_sub_f32_e32 v221, v221, v197
	v_exp_f32_e32 v218, v218
	v_exp_f32_e32 v219, v219
	v_exp_f32_e32 v220, v220
	v_exp_f32_e32 v221, v221
	s_waitcnt lgkmcnt(0)
	v_mfma_f32_32x32x16_bf16 v[66:81], v[206:209], v[98:101], v[66:81]
	v_sub_f32_e32 v222, v222, v197
	v_sub_f32_e32 v223, v223, v197
	v_sub_f32_e32 v224, v224, v197
	v_sub_f32_e32 v225, v225, v197
	v_exp_f32_e32 v222, v222
	v_exp_f32_e32 v223, v223
	v_exp_f32_e32 v224, v224
	v_exp_f32_e32 v225, v225
	v_mfma_f32_32x32x16_bf16 v[82:97], v[202:205], v[102:105], v[82:97]
	v_sub_f32_e32 v234, v234, v197
	v_sub_f32_e32 v235, v235, v197
	v_sub_f32_e32 v236, v236, v197
	v_sub_f32_e32 v237, v237, v197
	v_exp_f32_e32 v234, v234
	v_exp_f32_e32 v235, v235
	v_exp_f32_e32 v236, v236
	v_exp_f32_e32 v237, v237
	ds_read_b128 v[198:201], v0 offset:64
	ds_read_b128 v[202:205], v0 offset:96
	ds_read_b128 v[206:209], v0 offset:8768
	ds_read_b128 v[214:217], v0 offset:8800
	v_mfma_f32_32x32x16_bf16 v[66:81], v[210:213], v[102:105], v[66:81]
	v_add_f32_e32 v250, v218, v222
	v_add_f32_e32 v251, v219, v223
	v_add_f32_e32 v252, v220, v224
	v_add_f32_e32 v253, v221, v225
	v_sub_f32_e32 v238, v238, v197
	v_sub_f32_e32 v239, v239, v197
	v_sub_f32_e32 v240, v240, v197
	v_sub_f32_e32 v241, v241, v197
	s_waitcnt lgkmcnt(3)
	v_mfma_f32_32x32x16_bf16 v[82:97], v[198:201], v[106:109], v[82:97]
	v_exp_f32_e32 v238, v238
	v_exp_f32_e32 v239, v239
	v_exp_f32_e32 v240, v240
	v_exp_f32_e32 v241, v241
	v_add_f32_e32 v250, v250, v234
	v_add_f32_e32 v251, v251, v235
	v_add_f32_e32 v252, v252, v236
	v_add_f32_e32 v253, v253, v237
	s_waitcnt lgkmcnt(1)
	v_mfma_f32_32x32x16_bf16 v[66:81], v[206:209], v[106:109], v[66:81]
	v_sub_f32_e32 v226, v226, v197
	v_sub_f32_e32 v227, v227, v197
	v_sub_f32_e32 v228, v228, v197
	v_sub_f32_e32 v229, v229, v197
	v_exp_f32_e32 v226, v226
	v_exp_f32_e32 v227, v227
	v_exp_f32_e32 v228, v228
	v_exp_f32_e32 v229, v229
	v_mfma_f32_32x32x16_bf16 v[82:97], v[202:205], v[110:113], v[82:97]
	v_add_f32_e32 v250, v250, v238
	v_add_f32_e32 v251, v251, v239
	v_add_f32_e32 v252, v252, v240
	v_add_f32_e32 v253, v253, v241
	v_sub_f32_e32 v230, v230, v197
	v_sub_f32_e32 v231, v231, v197
	v_sub_f32_e32 v232, v232, v197
	v_sub_f32_e32 v233, v233, v197
	ds_read_b128 v[198:201], v0 offset:128
	ds_read_b128 v[202:205], v0 offset:160
	ds_read_b128 v[206:209], v0 offset:8832
	ds_read_b128 v[210:213], v0 offset:8864
	s_waitcnt lgkmcnt(4)
	v_mfma_f32_32x32x16_bf16 v[66:81], v[214:217], v[110:113], v[66:81]
	v_exp_f32_e32 v230, v230
	v_exp_f32_e32 v231, v231
	v_exp_f32_e32 v232, v232
	v_exp_f32_e32 v233, v233
	v_add_f32_e32 v250, v250, v226
	v_add_f32_e32 v251, v251, v227
	v_add_f32_e32 v252, v252, v228
	v_add_f32_e32 v253, v253, v229
	s_waitcnt lgkmcnt(3)
	v_mfma_f32_32x32x16_bf16 v[82:97], v[198:201], v[114:117], v[82:97]
	v_sub_f32_e32 v242, v242, v197
	v_sub_f32_e32 v243, v243, v197
	v_sub_f32_e32 v244, v244, v197
	v_sub_f32_e32 v245, v245, v197
	v_exp_f32_e32 v242, v242
	v_exp_f32_e32 v243, v243
	v_exp_f32_e32 v244, v244
	v_exp_f32_e32 v245, v245
	s_waitcnt lgkmcnt(1)
	v_mfma_f32_32x32x16_bf16 v[66:81], v[206:209], v[114:117], v[66:81]
	v_add_f32_e32 v250, v250, v230
	v_add_f32_e32 v251, v251, v231
	v_add_f32_e32 v252, v252, v232
	v_add_f32_e32 v253, v253, v233
	v_sub_f32_e32 v246, v246, v197
	v_sub_f32_e32 v247, v247, v197
	v_sub_f32_e32 v248, v248, v197
	v_sub_f32_e32 v249, v249, v197
	v_mfma_f32_32x32x16_bf16 v[82:97], v[202:205], v[118:121], v[82:97]
	v_exp_f32_e32 v246, v246
	v_exp_f32_e32 v247, v247
	v_exp_f32_e32 v248, v248
	v_exp_f32_e32 v249, v249
	v_add_f32_e32 v250, v250, v242
	v_add_f32_e32 v251, v251, v243
	v_add_f32_e32 v252, v252, v244
	v_add_f32_e32 v253, v253, v245
	ds_read_b128 v[198:201], v0 offset:192
	ds_read_b128 v[202:205], v0 offset:224
	ds_read_b128 v[206:209], v0 offset:8896
	ds_read_b128 v[214:217], v0 offset:8928
	s_waitcnt lgkmcnt(4)
	v_mfma_f32_32x32x16_bf16 v[66:81], v[210:213], v[118:121], v[66:81]
	v_add_f32_e32 v250, v250, v246
	v_add_f32_e32 v251, v251, v247
	v_add_f32_e32 v252, v252, v248
	v_add_f32_e32 v253, v253, v249
	v_add_f32_e32 v250, v250, v251
	v_add_f32_e32 v252, v252, v253
	v_add_f32_e32 v250, v250, v252
	v_add_f32_e32 v196, v196, v250
	s_waitcnt lgkmcnt(3)
	v_mfma_f32_32x32x16_bf16 v[82:97], v[198:201], v[122:125], v[82:97]
	v_cvt_pk_bf16_f32 v241, v240, v241
	v_cvt_pk_bf16_f32 v240, v238, v239
	v_cvt_pk_bf16_f32 v239, v236, v237
	v_cvt_pk_bf16_f32 v238, v234, v235
	v_cvt_pk_bf16_f32 v234, v218, v219
	v_cvt_pk_bf16_f32 v235, v220, v221
	v_cvt_pk_bf16_f32 v236, v222, v223
	v_cvt_pk_bf16_f32 v237, v224, v225
	s_waitcnt lgkmcnt(1)
	v_mfma_f32_32x32x16_bf16 v[66:81], v[206:209], v[122:125], v[66:81]
	v_cvt_pk_bf16_f32 v249, v248, v249
	v_cvt_pk_bf16_f32 v248, v246, v247
	v_cvt_pk_bf16_f32 v247, v244, v245
	v_cvt_pk_bf16_f32 v246, v242, v243
	v_cvt_pk_bf16_f32 v242, v226, v227
	v_cvt_pk_bf16_f32 v243, v228, v229
	v_cvt_pk_bf16_f32 v244, v230, v231
	v_cvt_pk_bf16_f32 v245, v232, v233
	v_mfma_f32_32x32x16_bf16 v[82:97], v[202:205], v[126:129], v[82:97]
	s_waitcnt lgkmcnt(0)
	v_mfma_f32_32x32x16_bf16 v[66:81], v[214:217], v[126:129], v[66:81]
	s_add_i32 s76, s77, 63
	s_cmp_le_i32 s76, s5
	s_cbranch_scc1 .Lff1b_z2
	v_cmp_le_i32_e32 vcc, v165, v195
	s_nop 8
	v_cndmask_b32_e32 v66, v155, v66, vcc
	v_cmp_lt_i32_e32 vcc, v163, v195
	s_nop 1
	v_cndmask_b32_e32 v83, v155, v83, vcc
	v_cmp_le_i32_e32 vcc, v163, v195
	s_nop 1
	v_cndmask_b32_e32 v82, v155, v82, vcc
	v_cmp_le_i32_e32 vcc, v166, v195
	s_nop 1
	v_cndmask_b32_e32 v67, v155, v67, vcc
	v_cmp_le_i32_e32 vcc, v167, v195
	s_nop 1
	v_cndmask_b32_e32 v84, v155, v84, vcc
	v_cmp_le_i32_e32 vcc, v168, v195
	s_nop 1
	v_cndmask_b32_e32 v68, v155, v68, vcc
	v_cmp_le_i32_e32 vcc, v169, v195
	s_nop 1
	v_cndmask_b32_e32 v85, v155, v85, vcc
	v_cmp_le_i32_e32 vcc, v170, v195
	s_nop 1
	v_cndmask_b32_e32 v69, v155, v69, vcc
	v_cmp_le_i32_e32 vcc, v171, v195
	s_nop 1
	v_cndmask_b32_e32 v86, v155, v86, vcc
	v_cmp_le_i32_e32 vcc, v172, v195
	s_nop 1
	v_cndmask_b32_e32 v70, v155, v70, vcc
	v_cmp_le_i32_e32 vcc, v173, v195
	s_nop 1
	v_cndmask_b32_e32 v87, v155, v87, vcc
	v_cmp_le_i32_e32 vcc, v174, v195
	s_nop 1
	v_cndmask_b32_e32 v71, v155, v71, vcc
	v_cmp_le_i32_e32 vcc, v175, v195
	s_nop 1
	v_cndmask_b32_e32 v88, v155, v88, vcc
	v_cmp_le_i32_e32 vcc, v176, v195
	s_nop 1
	v_cndmask_b32_e32 v72, v155, v72, vcc
	v_cmp_le_i32_e32 vcc, v177, v195
	s_nop 1
	v_cndmask_b32_e32 v89, v155, v89, vcc
	v_cmp_le_i32_e32 vcc, v178, v195
	s_nop 1
	v_cndmask_b32_e32 v73, v155, v73, vcc
	v_cmp_le_i32_e32 vcc, v179, v195
	s_nop 1
	v_cndmask_b32_e32 v90, v155, v90, vcc
	v_cmp_le_i32_e32 vcc, v180, v195
	s_nop 1
	v_cndmask_b32_e32 v74, v155, v74, vcc
	v_cmp_le_i32_e32 vcc, v181, v195
	s_nop 1
	v_cndmask_b32_e32 v91, v155, v91, vcc
	v_cmp_le_i32_e32 vcc, v182, v195
	s_nop 1
	v_cndmask_b32_e32 v75, v155, v75, vcc
	v_cmp_le_i32_e32 vcc, v183, v195
	s_nop 1
	v_cndmask_b32_e32 v92, v155, v92, vcc
	v_cmp_le_i32_e32 vcc, v184, v195
	s_nop 1
	v_cndmask_b32_e32 v76, v155, v76, vcc
	v_cmp_le_i32_e32 vcc, v185, v195
	s_nop 1
	v_cndmask_b32_e32 v93, v155, v93, vcc
	v_cmp_le_i32_e32 vcc, v186, v195
	s_nop 1
	v_cndmask_b32_e32 v77, v155, v77, vcc
	v_cmp_le_i32_e32 vcc, v187, v195
	s_nop 1
	v_cndmask_b32_e32 v94, v155, v94, vcc
	v_cmp_le_i32_e32 vcc, v188, v195
	s_nop 1
	v_cndmask_b32_e32 v78, v155, v78, vcc
	v_cmp_le_i32_e32 vcc, v189, v195
	s_nop 1
	v_cndmask_b32_e32 v95, v155, v95, vcc
	v_cmp_le_i32_e32 vcc, v190, v195
	s_nop 1
	v_cndmask_b32_e32 v79, v155, v79, vcc
	v_cmp_le_i32_e32 vcc, v191, v195
	s_nop 1
	v_cndmask_b32_e32 v96, v155, v96, vcc
	v_cmp_le_i32_e32 vcc, v192, v195
	s_nop 1
	v_cndmask_b32_e32 v80, v155, v80, vcc
	v_cmp_le_i32_e32 vcc, v193, v195
	s_nop 1
	v_cndmask_b32_e32 v97, v155, v97, vcc
	v_cmp_le_i32_e32 vcc, v194, v195
	s_nop 1
	v_cndmask_b32_e32 v81, v155, v81, vcc
